# final norm: two register sets, next row prefetched while the current row is reduced and stored
# speedup vs baseline: 1.0032x; 1.0032x over previous
; template <int M> DEVI float shx(float v) { return __int_as_float(__builtin_amdgcn_ds_swizzle(__float_as_int(v), (M << 10) | 0x1f)); }
; DEVI float shx32(float v, int lane) { return __int_as_float(__builtin_amdgcn_ds_bpermute((lane ^ 32) << 2, __float_as_int(v))); }
; __global__ void __launch_bounds__(512) mega(Params p) {
;     ...
;     for (int t = bid * 8 + wave; t < T; t += nblk * 8) {
;       float* r = xf + (size_t)t * DM;
;       const float* rin = ((t & 2047) == 0) ? (SX + (size_t)(t >> 11) * 1024) : r;
;       float4 v[4]; float ss = 0.f;
; #pragma unroll
;       for (int j = 0; j < 4; ++j) { v[j] = *(const float4*)(rin + j * 256 + lane * 4); ss += v[j].x * v[j].x + v[j].y * v[j].y + v[j].z * v[j].z + v[j].w * v[j].w; }
;       ss += shx32(ss, lane); ss += shx<16>(ss); ss += shx<8>(ss); ss += shx<4>(ss); ss += shx<2>(ss); ss += shx<1>(ss);
;       const float sc = rsqrtf(ss * (1.f / 1024.f) + 1e-6f);
; #pragma unroll
;       for (int j = 0; j < 4; ++j) {
;         const float4 g = *(const float4*)(fg + j * 256 + lane * 4);
;         float4 w; w.x = v[j].x * sc * g.x; w.y = v[j].y * sc * g.y; w.z = v[j].z * sc * g.z; w.w = v[j].w * sc * g.w;
;         *(float4*)(r + j * 256 + lane * 4) = w;
;       }
;     }
.LBB0_2241:
	v_readlane_b32 s0, v252, 46
	v_mbcnt_lo_u32_b32 v6, -1, 0
	v_mbcnt_hi_u32_b32 v6, -1, v6
	v_readlane_b32 s8, v253, 8
	v_readlane_b32 s9, v253, 9
	v_add_u32_e32 v0, s0, v6
	v_ashrrev_i32_e32 v4, 6, v0
	v_add_u32_e32 v8, s8, v4
	s_mov_b32 s0, 0x8000
	v_cmp_gt_i32_e32 vcc, s0, v8
	s_and_saveexec_b64 s[0:1], vcc
	v_readlane_b32 s10, v253, 12
	v_readlane_b32 s11, v253, 13
	s_cbranch_execz .LBB0_2244
	v_lshlrev_b32_e32 v0, 2, v6
	s_movk_i32 s0, 0x80
	v_bfrev_b32_e32 v2, 0.5
	v_bitop3_b32 v9, v0, s0, v2 bitop3:0x6c
	v_readlane_b32 s0, v252, 32
	v_and_b32_e32 v10, 0xfc, v0
	v_readlane_b32 s1, v252, 33
	v_readlane_b32 s2, v252, 34
	v_readlane_b32 s3, v252, 35
	v_ashrrev_i32_e32 v5, 31, v4
	s_ashr_i32 s9, s8, 31
	v_mov_b32_e32 v1, 0
	v_lshlrev_b32_e32 v0, 2, v10
	v_readlane_b32 s6, v252, 38
	v_readlane_b32 s7, v252, 39
	v_lshl_add_u64 v[4:5], v[4:5], 0, s[8:9]
	v_readlane_b32 s0, v252, 40
	v_readlane_b32 s4, v252, 36
	v_readlane_b32 s5, v252, 37
	v_lshl_add_u64 v[2:3], s[6:7], 0, v[0:1]
	v_lshlrev_b64 v[4:5], 12, v[4:5]
	v_readlane_b32 s1, v252, 41
	v_readlane_b32 s2, v252, 42
	v_readlane_b32 s3, v252, 43
	v_and_b32_e32 v0, 63, v6
	v_lshl_add_u64 v[4:5], s[0:1], 0, v[4:5]
	v_lshlrev_b32_e32 v0, 4, v0
	s_mov_b64 s[0:1], 0
	v_lshlrev_b32_e32 v6, 2, v10
	v_mov_b32_e32 v7, v1
	v_mov_b32_e32 v10, 0x358637bd
	s_mov_b32 s4, 0x800000
	s_mov_b64 s[2:3], 0x800000
	s_movk_i32 s5, 0x77ff
	global_load_dwordx4 v[50:53], v[2:3], off
	global_load_dwordx4 v[54:57], v[2:3], off offset:1024
	global_load_dwordx4 v[58:61], v[2:3], off offset:2048
	global_load_dwordx4 v[62:65], v[2:3], off offset:3072
	v_ashrrev_i32_e32 v82, 11, v8
	v_ashrrev_i32_e32 v83, 31, v82
	v_and_b32_e32 v11, 0x7ff, v8
	v_lshlrev_b64 v[82:83], 12, v[82:83]
	v_lshl_add_u64 v[82:83], s[10:11], 0, v[82:83]
	v_cmp_eq_u32_e32 vcc, 0, v11
	s_nop 1
	v_cndmask_b32_e32 v83, v5, v83, vcc
	v_cndmask_b32_e32 v82, v4, v82, vcc
	v_lshl_add_u64 v[82:83], v[82:83], 0, v[6:7]
	global_load_dwordx4 v[12:15], v[82:83], off
	global_load_dwordx4 v[16:19], v[82:83], off offset:1024
	global_load_dwordx4 v[20:23], v[82:83], off offset:2048
	global_load_dwordx4 v[24:27], v[82:83], off offset:3072
	s_waitcnt vmcnt(0)
	s_mov_b32 s5, 0
.LBB0_2243:
	v_add_u32_e32 v8, 0x800, v8
	v_ashrrev_i32_e32 v82, 11, v8
	v_ashrrev_i32_e32 v83, 31, v82
	v_and_b32_e32 v11, 0x7ff, v8
	v_lshlrev_b64 v[82:83], 12, v[82:83]
	v_lshl_add_u64 v[82:83], s[10:11], 0, v[82:83]
	v_lshl_add_u64 v[84:85], v[4:5], 0, s[2:3]
	v_cmp_eq_u32_e32 vcc, 0, v11
	s_nop 1
	v_cndmask_b32_e32 v83, v85, v83, vcc
	v_cndmask_b32_e32 v82, v84, v82, vcc
	v_lshl_add_u64 v[82:83], v[82:83], 0, v[6:7]
	global_load_dwordx4 v[66:69], v[82:83], off
	global_load_dwordx4 v[70:73], v[82:83], off offset:1024
	global_load_dwordx4 v[74:77], v[82:83], off offset:2048
	global_load_dwordx4 v[78:81], v[82:83], off offset:3072
	s_waitcnt vmcnt(8)
	v_lshl_add_u64 v[32:33], v[4:5], 0, v[0:1]
	v_mov_b32_e32 v36, v13
	v_mov_b32_e32 v37, v17
	v_mov_b32_e32 v34, v12
	v_mov_b32_e32 v35, v16
	v_mov_b32_e32 v44, v21
	v_mov_b32_e32 v45, v25
	v_pk_mul_f32 v[36:37], v[36:37], v[36:37]
	v_mov_b32_e32 v38, v14
	v_mov_b32_e32 v39, v18
	v_mov_b32_e32 v42, v20
	v_mov_b32_e32 v43, v24
	v_pk_mul_f32 v[44:45], v[44:45], v[44:45]
	v_pk_fma_f32 v[34:35], v[34:35], v[34:35], v[36:37]
	v_mov_b32_e32 v40, v15
	v_mov_b32_e32 v41, v19
	v_mov_b32_e32 v46, v22
	v_mov_b32_e32 v47, v26
	v_pk_fma_f32 v[36:37], v[42:43], v[42:43], v[44:45]
	v_pk_fma_f32 v[34:35], v[38:39], v[38:39], v[34:35]
	v_mov_b32_e32 v48, v23
	v_mov_b32_e32 v49, v27
	v_pk_fma_f32 v[36:37], v[46:47], v[46:47], v[36:37]
	v_pk_fma_f32 v[34:35], v[40:41], v[40:41], v[34:35]
	v_pk_fma_f32 v[36:37], v[48:49], v[48:49], v[36:37]
	v_add_f32_e32 v11, v34, v35
	v_add_f32_e32 v11, v11, v36
	v_add_f32_e32 v11, v11, v37
	ds_bpermute_b32 v34, v9, v11
	s_waitcnt lgkmcnt(0)
	v_add_f32_e32 v11, v11, v34
	ds_swizzle_b32 v34, v11 offset:swizzle(SWAP,16)
	s_waitcnt lgkmcnt(0)
	v_add_f32_e32 v11, v11, v34
	ds_swizzle_b32 v34, v11 offset:swizzle(SWAP,8)
	s_waitcnt lgkmcnt(0)
	v_add_f32_e32 v11, v11, v34
	ds_swizzle_b32 v34, v11 offset:swizzle(SWAP,4)
	s_waitcnt lgkmcnt(0)
	v_add_f32_e32 v11, v11, v34
	ds_swizzle_b32 v34, v11 offset:swizzle(SWAP,2)
	s_waitcnt lgkmcnt(0)
	v_add_f32_e32 v11, v11, v34
	ds_swizzle_b32 v34, v11 offset:swizzle(SWAP,1)
	s_waitcnt lgkmcnt(0)
	v_add_f32_e32 v11, v11, v34
	v_fmamk_f32 v11, v11, 0x3a800000, v10
	v_mul_f32_e32 v34, 0x4b800000, v11
	v_cmp_gt_f32_e32 vcc, s4, v11
	s_nop 1
	v_cndmask_b32_e32 v11, v11, v34, vcc
	v_rsq_f32_e32 v11, v11
	s_nop 0
	v_mul_f32_e32 v34, 0x45800000, v11
	v_cndmask_b32_e32 v34, v11, v34, vcc
	v_pk_mul_f32 v[12:13], v[34:35], v[12:13] op_sel_hi:[0,1]
	v_pk_mul_f32 v[14:15], v[34:35], v[14:15] op_sel_hi:[0,1]
	v_pk_mul_f32 v[12:13], v[50:51], v[12:13]
	v_pk_mul_f32 v[14:15], v[52:53], v[14:15]
	global_store_dwordx4 v[32:33], v[12:15], off
	v_pk_mul_f32 v[16:17], v[34:35], v[16:17] op_sel_hi:[0,1]
	v_pk_mul_f32 v[18:19], v[34:35], v[18:19] op_sel_hi:[0,1]
	v_pk_mul_f32 v[16:17], v[54:55], v[16:17]
	v_pk_mul_f32 v[18:19], v[56:57], v[18:19]
	global_store_dwordx4 v[32:33], v[16:19], off offset:1024
	v_pk_mul_f32 v[20:21], v[34:35], v[20:21] op_sel_hi:[0,1]
	v_pk_mul_f32 v[22:23], v[34:35], v[22:23] op_sel_hi:[0,1]
	v_pk_mul_f32 v[20:21], v[58:59], v[20:21]
	v_pk_mul_f32 v[22:23], v[60:61], v[22:23]
	global_store_dwordx4 v[32:33], v[20:23], off offset:2048
	v_pk_mul_f32 v[24:25], v[34:35], v[24:25] op_sel_hi:[0,1]
	v_pk_mul_f32 v[26:27], v[34:35], v[26:27] op_sel_hi:[0,1]
	v_pk_mul_f32 v[24:25], v[62:63], v[24:25]
	v_pk_mul_f32 v[26:27], v[64:65], v[26:27]
	global_store_dwordx4 v[32:33], v[24:27], off offset:3072
	v_mov_b32_e32 v4, v84
	v_mov_b32_e32 v5, v85
	v_add_u32_e32 v8, 0x800, v8
	v_ashrrev_i32_e32 v82, 11, v8
	v_ashrrev_i32_e32 v83, 31, v82
	v_and_b32_e32 v11, 0x7ff, v8
	v_lshlrev_b64 v[82:83], 12, v[82:83]
	v_lshl_add_u64 v[82:83], s[10:11], 0, v[82:83]
	v_lshl_add_u64 v[84:85], v[4:5], 0, s[2:3]
	v_cmp_eq_u32_e32 vcc, 0, v11
	s_nop 1
	v_cndmask_b32_e32 v83, v85, v83, vcc
	v_cndmask_b32_e32 v82, v84, v82, vcc
	v_lshl_add_u64 v[82:83], v[82:83], 0, v[6:7]
	global_load_dwordx4 v[12:15], v[82:83], off
	global_load_dwordx4 v[16:19], v[82:83], off offset:1024
	global_load_dwordx4 v[20:23], v[82:83], off offset:2048
	global_load_dwordx4 v[24:27], v[82:83], off offset:3072
	s_waitcnt vmcnt(8)
; template <int M> DEVI float shx(float v) { return __int_as_float(__builtin_amdgcn_ds_swizzle(__float_as_int(v), (M << 10) | 0x1f)); }
; DEVI float shx32(float v, int lane) { return __int_as_float(__builtin_amdgcn_ds_bpermute((lane ^ 32) << 2, __float_as_int(v))); }
; __global__ void __launch_bounds__(512) mega(Params p) {
;     ...
;     for (int t = bid * 8 + wave; t < T; t += nblk * 8) {
;       float* r = xf + (size_t)t * DM;
;       const float* rin = ((t & 2047) == 0) ? (SX + (size_t)(t >> 11) * 1024) : r;
;       float4 v[4]; float ss = 0.f;
; #pragma unroll
;       for (int j = 0; j < 4; ++j) { v[j] = *(const float4*)(rin + j * 256 + lane * 4); ss += v[j].x * v[j].x + v[j].y * v[j].y + v[j].z * v[j].z + v[j].w * v[j].w; }
;       ss += shx32(ss, lane); ss += shx<16>(ss); ss += shx<8>(ss); ss += shx<4>(ss); ss += shx<2>(ss); ss += shx<1>(ss);
;       const float sc = rsqrtf(ss * (1.f / 1024.f) + 1e-6f);
; #pragma unroll
;       for (int j = 0; j < 4; ++j) {
;         const float4 g = *(const float4*)(fg + j * 256 + lane * 4);
;         float4 w; w.x = v[j].x * sc * g.x; w.y = v[j].y * sc * g.y; w.z = v[j].z * sc * g.z; w.w = v[j].w * sc * g.w;
;         *(float4*)(r + j * 256 + lane * 4) = w;
;       }
;     }
	v_lshl_add_u64 v[32:33], v[4:5], 0, v[0:1]
	v_mov_b32_e32 v36, v67
	v_mov_b32_e32 v37, v71
	v_mov_b32_e32 v34, v66
	v_mov_b32_e32 v35, v70
	v_mov_b32_e32 v44, v75
	v_mov_b32_e32 v45, v79
	v_pk_mul_f32 v[36:37], v[36:37], v[36:37]
	v_mov_b32_e32 v38, v68
	v_mov_b32_e32 v39, v72
	v_mov_b32_e32 v42, v74
	v_mov_b32_e32 v43, v78
	v_pk_mul_f32 v[44:45], v[44:45], v[44:45]
	v_pk_fma_f32 v[34:35], v[34:35], v[34:35], v[36:37]
	v_mov_b32_e32 v40, v69
	v_mov_b32_e32 v41, v73
	v_mov_b32_e32 v46, v76
	v_mov_b32_e32 v47, v80
	v_pk_fma_f32 v[36:37], v[42:43], v[42:43], v[44:45]
	v_pk_fma_f32 v[34:35], v[38:39], v[38:39], v[34:35]
	v_mov_b32_e32 v48, v77
	v_mov_b32_e32 v49, v81
	v_pk_fma_f32 v[36:37], v[46:47], v[46:47], v[36:37]
	v_pk_fma_f32 v[34:35], v[40:41], v[40:41], v[34:35]
	v_pk_fma_f32 v[36:37], v[48:49], v[48:49], v[36:37]
	v_add_f32_e32 v11, v34, v35
	v_add_f32_e32 v11, v11, v36
	v_add_f32_e32 v11, v11, v37
	ds_bpermute_b32 v34, v9, v11
	s_waitcnt lgkmcnt(0)
	v_add_f32_e32 v11, v11, v34
	ds_swizzle_b32 v34, v11 offset:swizzle(SWAP,16)
	s_waitcnt lgkmcnt(0)
	v_add_f32_e32 v11, v11, v34
	ds_swizzle_b32 v34, v11 offset:swizzle(SWAP,8)
	s_waitcnt lgkmcnt(0)
	v_add_f32_e32 v11, v11, v34
	ds_swizzle_b32 v34, v11 offset:swizzle(SWAP,4)
	s_waitcnt lgkmcnt(0)
	v_add_f32_e32 v11, v11, v34
	ds_swizzle_b32 v34, v11 offset:swizzle(SWAP,2)
	s_waitcnt lgkmcnt(0)
	v_add_f32_e32 v11, v11, v34
	ds_swizzle_b32 v34, v11 offset:swizzle(SWAP,1)
	s_waitcnt lgkmcnt(0)
	v_add_f32_e32 v11, v11, v34
	v_fmamk_f32 v11, v11, 0x3a800000, v10
	v_mul_f32_e32 v34, 0x4b800000, v11
	v_cmp_gt_f32_e32 vcc, s4, v11
	s_nop 1
	v_cndmask_b32_e32 v11, v11, v34, vcc
	v_rsq_f32_e32 v11, v11
	s_nop 0
	v_mul_f32_e32 v34, 0x45800000, v11
	v_cndmask_b32_e32 v34, v11, v34, vcc
	v_pk_mul_f32 v[66:67], v[34:35], v[66:67] op_sel_hi:[0,1]
	v_pk_mul_f32 v[68:69], v[34:35], v[68:69] op_sel_hi:[0,1]
	v_pk_mul_f32 v[66:67], v[50:51], v[66:67]
	v_pk_mul_f32 v[68:69], v[52:53], v[68:69]
	global_store_dwordx4 v[32:33], v[66:69], off
	v_pk_mul_f32 v[70:71], v[34:35], v[70:71] op_sel_hi:[0,1]
	v_pk_mul_f32 v[72:73], v[34:35], v[72:73] op_sel_hi:[0,1]
	v_pk_mul_f32 v[70:71], v[54:55], v[70:71]
	v_pk_mul_f32 v[72:73], v[56:57], v[72:73]
	global_store_dwordx4 v[32:33], v[70:73], off offset:1024
	v_pk_mul_f32 v[74:75], v[34:35], v[74:75] op_sel_hi:[0,1]
	v_pk_mul_f32 v[76:77], v[34:35], v[76:77] op_sel_hi:[0,1]
	v_pk_mul_f32 v[74:75], v[58:59], v[74:75]
	v_pk_mul_f32 v[76:77], v[60:61], v[76:77]
	global_store_dwordx4 v[32:33], v[74:77], off offset:2048
	v_pk_mul_f32 v[78:79], v[34:35], v[78:79] op_sel_hi:[0,1]
	v_pk_mul_f32 v[80:81], v[34:35], v[80:81] op_sel_hi:[0,1]
	v_pk_mul_f32 v[78:79], v[62:63], v[78:79]
	v_pk_mul_f32 v[80:81], v[64:65], v[80:81]
	global_store_dwordx4 v[32:33], v[78:81], off offset:3072
	v_mov_b32_e32 v4, v84
	v_mov_b32_e32 v5, v85
	s_add_i32 s5, s5, 1
	s_cmp_lt_u32 s5, 7
	s_cbranch_scc1 .LBB0_2243
; template <int M> DEVI float shx(float v) { return __int_as_float(__builtin_amdgcn_ds_swizzle(__float_as_int(v), (M << 10) | 0x1f)); }
; DEVI float shx32(float v, int lane) { return __int_as_float(__builtin_amdgcn_ds_bpermute((lane ^ 32) << 2, __float_as_int(v))); }
; __global__ void __launch_bounds__(512) mega(Params p) {
;     ...
;     for (int t = bid * 8 + wave; t < T; t += nblk * 8) {
;       float* r = xf + (size_t)t * DM;
;       const float* rin = ((t & 2047) == 0) ? (SX + (size_t)(t >> 11) * 1024) : r;
;       float4 v[4]; float ss = 0.f;
; #pragma unroll
;       for (int j = 0; j < 4; ++j) { v[j] = *(const float4*)(rin + j * 256 + lane * 4); ss += v[j].x * v[j].x + v[j].y * v[j].y + v[j].z * v[j].z + v[j].w * v[j].w; }
;       ss += shx32(ss, lane); ss += shx<16>(ss); ss += shx<8>(ss); ss += shx<4>(ss); ss += shx<2>(ss); ss += shx<1>(ss);
;       const float sc = rsqrtf(ss * (1.f / 1024.f) + 1e-6f);
; #pragma unroll
;       for (int j = 0; j < 4; ++j) {
;         const float4 g = *(const float4*)(fg + j * 256 + lane * 4);
;         float4 w; w.x = v[j].x * sc * g.x; w.y = v[j].y * sc * g.y; w.z = v[j].z * sc * g.z; w.w = v[j].w * sc * g.w;
;         *(float4*)(r + j * 256 + lane * 4) = w;
;       }
;     }
	v_add_u32_e32 v8, 0x800, v8
	v_ashrrev_i32_e32 v82, 11, v8
	v_ashrrev_i32_e32 v83, 31, v82
	v_and_b32_e32 v11, 0x7ff, v8
	v_lshlrev_b64 v[82:83], 12, v[82:83]
	v_lshl_add_u64 v[82:83], s[10:11], 0, v[82:83]
	v_lshl_add_u64 v[84:85], v[4:5], 0, s[2:3]
	v_cmp_eq_u32_e32 vcc, 0, v11
	s_nop 1
	v_cndmask_b32_e32 v83, v85, v83, vcc
	v_cndmask_b32_e32 v82, v84, v82, vcc
	v_lshl_add_u64 v[82:83], v[82:83], 0, v[6:7]
	global_load_dwordx4 v[66:69], v[82:83], off
	global_load_dwordx4 v[70:73], v[82:83], off offset:1024
	global_load_dwordx4 v[74:77], v[82:83], off offset:2048
	global_load_dwordx4 v[78:81], v[82:83], off offset:3072
	s_waitcnt vmcnt(8)
	v_lshl_add_u64 v[32:33], v[4:5], 0, v[0:1]
	v_mov_b32_e32 v36, v13
	v_mov_b32_e32 v37, v17
	v_mov_b32_e32 v34, v12
	v_mov_b32_e32 v35, v16
	v_mov_b32_e32 v44, v21
	v_mov_b32_e32 v45, v25
	v_pk_mul_f32 v[36:37], v[36:37], v[36:37]
	v_mov_b32_e32 v38, v14
	v_mov_b32_e32 v39, v18
	v_mov_b32_e32 v42, v20
	v_mov_b32_e32 v43, v24
	v_pk_mul_f32 v[44:45], v[44:45], v[44:45]
	v_pk_fma_f32 v[34:35], v[34:35], v[34:35], v[36:37]
	v_mov_b32_e32 v40, v15
	v_mov_b32_e32 v41, v19
	v_mov_b32_e32 v46, v22
	v_mov_b32_e32 v47, v26
	v_pk_fma_f32 v[36:37], v[42:43], v[42:43], v[44:45]
	v_pk_fma_f32 v[34:35], v[38:39], v[38:39], v[34:35]
	v_mov_b32_e32 v48, v23
	v_mov_b32_e32 v49, v27
	v_pk_fma_f32 v[36:37], v[46:47], v[46:47], v[36:37]
	v_pk_fma_f32 v[34:35], v[40:41], v[40:41], v[34:35]
	v_pk_fma_f32 v[36:37], v[48:49], v[48:49], v[36:37]
	v_add_f32_e32 v11, v34, v35
	v_add_f32_e32 v11, v11, v36
	v_add_f32_e32 v11, v11, v37
	ds_bpermute_b32 v34, v9, v11
	s_waitcnt lgkmcnt(0)
	v_add_f32_e32 v11, v11, v34
	ds_swizzle_b32 v34, v11 offset:swizzle(SWAP,16)
	s_waitcnt lgkmcnt(0)
	v_add_f32_e32 v11, v11, v34
	ds_swizzle_b32 v34, v11 offset:swizzle(SWAP,8)
	s_waitcnt lgkmcnt(0)
	v_add_f32_e32 v11, v11, v34
	ds_swizzle_b32 v34, v11 offset:swizzle(SWAP,4)
	s_waitcnt lgkmcnt(0)
	v_add_f32_e32 v11, v11, v34
	ds_swizzle_b32 v34, v11 offset:swizzle(SWAP,2)
	s_waitcnt lgkmcnt(0)
	v_add_f32_e32 v11, v11, v34
	ds_swizzle_b32 v34, v11 offset:swizzle(SWAP,1)
	s_waitcnt lgkmcnt(0)
	v_add_f32_e32 v11, v11, v34
	v_fmamk_f32 v11, v11, 0x3a800000, v10
	v_mul_f32_e32 v34, 0x4b800000, v11
	v_cmp_gt_f32_e32 vcc, s4, v11
	s_nop 1
	v_cndmask_b32_e32 v11, v11, v34, vcc
	v_rsq_f32_e32 v11, v11
	s_nop 0
	v_mul_f32_e32 v34, 0x45800000, v11
	v_cndmask_b32_e32 v34, v11, v34, vcc
	v_pk_mul_f32 v[12:13], v[34:35], v[12:13] op_sel_hi:[0,1]
	v_pk_mul_f32 v[14:15], v[34:35], v[14:15] op_sel_hi:[0,1]
	v_pk_mul_f32 v[12:13], v[50:51], v[12:13]
	v_pk_mul_f32 v[14:15], v[52:53], v[14:15]
	global_store_dwordx4 v[32:33], v[12:15], off
	v_pk_mul_f32 v[16:17], v[34:35], v[16:17] op_sel_hi:[0,1]
	v_pk_mul_f32 v[18:19], v[34:35], v[18:19] op_sel_hi:[0,1]
	v_pk_mul_f32 v[16:17], v[54:55], v[16:17]
	v_pk_mul_f32 v[18:19], v[56:57], v[18:19]
	global_store_dwordx4 v[32:33], v[16:19], off offset:1024
	v_pk_mul_f32 v[20:21], v[34:35], v[20:21] op_sel_hi:[0,1]
	v_pk_mul_f32 v[22:23], v[34:35], v[22:23] op_sel_hi:[0,1]
	v_pk_mul_f32 v[20:21], v[58:59], v[20:21]
	v_pk_mul_f32 v[22:23], v[60:61], v[22:23]
	global_store_dwordx4 v[32:33], v[20:23], off offset:2048
	v_pk_mul_f32 v[24:25], v[34:35], v[24:25] op_sel_hi:[0,1]
	v_pk_mul_f32 v[26:27], v[34:35], v[26:27] op_sel_hi:[0,1]
	v_pk_mul_f32 v[24:25], v[62:63], v[24:25]
	v_pk_mul_f32 v[26:27], v[64:65], v[26:27]
	global_store_dwordx4 v[32:33], v[24:27], off offset:3072
	v_mov_b32_e32 v4, v84
	v_mov_b32_e32 v5, v85
	s_waitcnt vmcnt(4)
	v_lshl_add_u64 v[32:33], v[4:5], 0, v[0:1]
	v_mov_b32_e32 v36, v67
	v_mov_b32_e32 v37, v71
	v_mov_b32_e32 v34, v66
	v_mov_b32_e32 v35, v70
	v_mov_b32_e32 v44, v75
	v_mov_b32_e32 v45, v79
	v_pk_mul_f32 v[36:37], v[36:37], v[36:37]
	v_mov_b32_e32 v38, v68
	v_mov_b32_e32 v39, v72
	v_mov_b32_e32 v42, v74
	v_mov_b32_e32 v43, v78
	v_pk_mul_f32 v[44:45], v[44:45], v[44:45]
	v_pk_fma_f32 v[34:35], v[34:35], v[34:35], v[36:37]
	v_mov_b32_e32 v40, v69
	v_mov_b32_e32 v41, v73
	v_mov_b32_e32 v46, v76
	v_mov_b32_e32 v47, v80
	v_pk_fma_f32 v[36:37], v[42:43], v[42:43], v[44:45]
	v_pk_fma_f32 v[34:35], v[38:39], v[38:39], v[34:35]
	v_mov_b32_e32 v48, v77
	v_mov_b32_e32 v49, v81
	v_pk_fma_f32 v[36:37], v[46:47], v[46:47], v[36:37]
	v_pk_fma_f32 v[34:35], v[40:41], v[40:41], v[34:35]
	v_pk_fma_f32 v[36:37], v[48:49], v[48:49], v[36:37]
	v_add_f32_e32 v11, v34, v35
	v_add_f32_e32 v11, v11, v36
	v_add_f32_e32 v11, v11, v37
	ds_bpermute_b32 v34, v9, v11
	s_waitcnt lgkmcnt(0)
	v_add_f32_e32 v11, v11, v34
	ds_swizzle_b32 v34, v11 offset:swizzle(SWAP,16)
	s_waitcnt lgkmcnt(0)
	v_add_f32_e32 v11, v11, v34
	ds_swizzle_b32 v34, v11 offset:swizzle(SWAP,8)
	s_waitcnt lgkmcnt(0)
	v_add_f32_e32 v11, v11, v34
	ds_swizzle_b32 v34, v11 offset:swizzle(SWAP,4)
	s_waitcnt lgkmcnt(0)
	v_add_f32_e32 v11, v11, v34
	ds_swizzle_b32 v34, v11 offset:swizzle(SWAP,2)
	s_waitcnt lgkmcnt(0)
	v_add_f32_e32 v11, v11, v34
	ds_swizzle_b32 v34, v11 offset:swizzle(SWAP,1)
	s_waitcnt lgkmcnt(0)
	v_add_f32_e32 v11, v11, v34
	v_fmamk_f32 v11, v11, 0x3a800000, v10
	v_mul_f32_e32 v34, 0x4b800000, v11
	v_cmp_gt_f32_e32 vcc, s4, v11
	s_nop 1
	v_cndmask_b32_e32 v11, v11, v34, vcc
	v_rsq_f32_e32 v11, v11
	s_nop 0
	v_mul_f32_e32 v34, 0x45800000, v11
	v_cndmask_b32_e32 v34, v11, v34, vcc
	v_pk_mul_f32 v[66:67], v[34:35], v[66:67] op_sel_hi:[0,1]
	v_pk_mul_f32 v[68:69], v[34:35], v[68:69] op_sel_hi:[0,1]
	v_pk_mul_f32 v[66:67], v[50:51], v[66:67]
	v_pk_mul_f32 v[68:69], v[52:53], v[68:69]
	global_store_dwordx4 v[32:33], v[66:69], off
	v_pk_mul_f32 v[70:71], v[34:35], v[70:71] op_sel_hi:[0,1]
	v_pk_mul_f32 v[72:73], v[34:35], v[72:73] op_sel_hi:[0,1]
	v_pk_mul_f32 v[70:71], v[54:55], v[70:71]
	v_pk_mul_f32 v[72:73], v[56:57], v[72:73]
	global_store_dwordx4 v[32:33], v[70:73], off offset:1024
	v_pk_mul_f32 v[74:75], v[34:35], v[74:75] op_sel_hi:[0,1]
	v_pk_mul_f32 v[76:77], v[34:35], v[76:77] op_sel_hi:[0,1]
	v_pk_mul_f32 v[74:75], v[58:59], v[74:75]
	v_pk_mul_f32 v[76:77], v[60:61], v[76:77]
	global_store_dwordx4 v[32:33], v[74:77], off offset:2048
	v_pk_mul_f32 v[78:79], v[34:35], v[78:79] op_sel_hi:[0,1]
	v_pk_mul_f32 v[80:81], v[34:35], v[80:81] op_sel_hi:[0,1]
	v_pk_mul_f32 v[78:79], v[62:63], v[78:79]
	v_pk_mul_f32 v[80:81], v[64:65], v[80:81]
	global_store_dwordx4 v[32:33], v[78:81], off offset:3072
